# adds: L6b gemm_tile k-loop with 2-deep register prefetch and batched LDS reads; L6b gate-tile loads issued together instead of 8 serialized round trips
# speedup vs baseline: 1.0521x; 1.0082x over previous
.LBB0_1865:
	s_add_i32 s14, s24, -1
	v_lshl_add_u64 v[164:165], v[114:115], 0, v[128:129]
	v_lshl_add_u64 v[168:169], v[74:75], 0, v[128:129]
	v_lshl_add_u64 v[172:173], v[112:113], 0, v[128:129]
	v_lshl_add_u64 v[180:181], v[72:73], 0, v[128:129]
	v_lshl_add_u64 v[184:185], v[76:77], 0, v[128:129]
	v_lshl_add_u64 v[188:189], v[68:69], 0, v[128:129]
	v_lshl_add_u64 v[192:193], v[78:79], 0, v[128:129]
	v_lshl_add_u64 v[196:197], v[70:71], 0, v[128:129]
	global_load_dwordx4 v[164:167], v[164:165], off
	global_load_dwordx4 v[168:171], v[168:169], off
	global_load_dwordx4 v[172:175], v[172:173], off
	global_load_dwordx4 v[180:183], v[180:181], off
	global_load_dwordx4 v[184:187], v[184:185], off
	global_load_dwordx4 v[188:191], v[188:189], off
	global_load_dwordx4 v[192:195], v[192:193], off
	global_load_dwordx4 v[196:199], v[196:197], off
.Lgt_top:
	s_and_b32 s15, s2, 1
	s_mul_i32 s15, s15, 0x4800
	v_add_u32_e32 v248, s15, v64
	v_add_u32_e32 v249, s15, v65
	s_xor_b32 s15, s15, 0x4800
	v_add_u32_e32 v200, s15, v66
	ds_read_b128 v[116:119], v248
	ds_read_b128 v[120:123], v248 offset:4608
	ds_read_b128 v[124:127], v249 offset:36864
	ds_read_b128 v[228:231], v249 offset:41472
	v_lshl_add_u64 v[130:131], v[114:115], 0, v[128:129]
	v_lshl_add_u64 v[134:135], v[74:75], 0, v[128:129]
	v_lshl_add_u64 v[138:139], v[112:113], 0, v[128:129]
	v_lshl_add_u64 v[142:143], v[72:73], 0, v[128:129]
	v_lshl_add_u64 v[146:147], v[76:77], 0, v[128:129]
	v_lshl_add_u64 v[150:151], v[68:69], 0, v[128:129]
	v_lshl_add_u64 v[154:155], v[78:79], 0, v[128:129]
	v_lshl_add_u64 v[158:159], v[70:71], 0, v[128:129]
	global_load_dwordx4 v[130:133], v[130:131], off offset:128
	global_load_dwordx4 v[134:137], v[134:135], off offset:128
	global_load_dwordx4 v[138:141], v[138:139], off offset:128
	global_load_dwordx4 v[142:145], v[142:143], off offset:128
	global_load_dwordx4 v[146:149], v[146:147], off offset:128
	global_load_dwordx4 v[150:153], v[150:151], off offset:128
	global_load_dwordx4 v[154:157], v[154:155], off offset:128
	global_load_dwordx4 v[158:161], v[158:159], off offset:128
	v_lshl_add_u64 v[114:115], v[114:115], 0, s[68:69]
	v_lshl_add_u64 v[74:75], v[74:75], 0, s[68:69]
	v_lshl_add_u64 v[112:113], v[112:113], 0, s[68:69]
	v_lshl_add_u64 v[72:73], v[72:73], 0, s[68:69]
	v_lshl_add_u64 v[76:77], v[76:77], 0, s[68:69]
	v_lshl_add_u64 v[68:69], v[68:69], 0, s[68:69]
	v_lshl_add_u64 v[78:79], v[78:79], 0, s[68:69]
	v_lshl_add_u64 v[70:71], v[70:71], 0, s[68:69]
	ds_read_b128 v[232:235], v248 offset:32
	ds_read_b128 v[236:239], v248 offset:4640
	ds_read_b128 v[240:243], v249 offset:36896
	ds_read_b128 v[244:247], v249 offset:41504
	s_waitcnt lgkmcnt(5)
	v_mfma_f32_32x32x16_bf16 v[48:63], v[116:119], v[124:127], v[48:63]
	s_waitcnt lgkmcnt(4)
	v_mfma_f32_32x32x16_bf16 v[16:31], v[116:119], v[228:231], v[16:31]
	s_waitcnt lgkmcnt(5)
	v_mfma_f32_32x32x16_bf16 v[32:47], v[120:123], v[124:127], v[32:47]
	s_waitcnt lgkmcnt(4)
	v_mfma_f32_32x32x16_bf16 v[0:15], v[120:123], v[228:231], v[0:15]
	ds_read_b128 v[116:119], v248 offset:64
	ds_read_b128 v[120:123], v248 offset:4672
	ds_read_b128 v[124:127], v249 offset:36928
	ds_read_b128 v[228:231], v249 offset:41536
	s_waitcnt lgkmcnt(5)
	v_mfma_f32_32x32x16_bf16 v[48:63], v[232:235], v[240:243], v[48:63]
	s_waitcnt lgkmcnt(4)
	v_mfma_f32_32x32x16_bf16 v[16:31], v[232:235], v[244:247], v[16:31]
	s_waitcnt lgkmcnt(5)
	v_mfma_f32_32x32x16_bf16 v[32:47], v[236:239], v[240:243], v[32:47]
	s_waitcnt lgkmcnt(4)
	v_mfma_f32_32x32x16_bf16 v[0:15], v[236:239], v[244:247], v[0:15]
	ds_read_b128 v[232:235], v248 offset:96
	ds_read_b128 v[236:239], v248 offset:4704
	ds_read_b128 v[240:243], v249 offset:36960
	ds_read_b128 v[244:247], v249 offset:41568
	s_waitcnt vmcnt(8) lgkmcnt(5)
	v_mfma_f32_32x32x16_bf16 v[48:63], v[116:119], v[124:127], v[48:63]
	ds_write_b128 v200, v[164:167]
	s_waitcnt lgkmcnt(5)
	v_mfma_f32_32x32x16_bf16 v[16:31], v[116:119], v[228:231], v[16:31]
	ds_write_b128 v200, v[168:171] offset:36864
	s_waitcnt lgkmcnt(7)
	v_mfma_f32_32x32x16_bf16 v[32:47], v[120:123], v[124:127], v[32:47]
	ds_write_b128 v200, v[172:175] offset:4608
	s_waitcnt lgkmcnt(7)
	v_mfma_f32_32x32x16_bf16 v[0:15], v[120:123], v[228:231], v[0:15]
	ds_write_b128 v200, v[180:183] offset:41472
	s_waitcnt lgkmcnt(5)
	v_mfma_f32_32x32x16_bf16 v[48:63], v[232:235], v[240:243], v[48:63]
	ds_write_b128 v200, v[184:187] offset:9216
	s_waitcnt lgkmcnt(5)
	v_mfma_f32_32x32x16_bf16 v[16:31], v[232:235], v[244:247], v[16:31]
	ds_write_b128 v200, v[188:191] offset:46080
	s_waitcnt lgkmcnt(7)
	v_mfma_f32_32x32x16_bf16 v[32:47], v[236:239], v[240:243], v[32:47]
	ds_write_b128 v200, v[192:195] offset:13824
	s_waitcnt lgkmcnt(7)
	v_mfma_f32_32x32x16_bf16 v[0:15], v[236:239], v[244:247], v[0:15]
	ds_write_b128 v200, v[196:199] offset:50688
	s_waitcnt lgkmcnt(0)
	s_barrier
	s_add_i32 s2, s2, 1
	s_and_b32 s15, s2, 1
	s_mul_i32 s15, s15, 0x4800
	v_add_u32_e32 v248, s15, v64
	v_add_u32_e32 v249, s15, v65
	s_xor_b32 s15, s15, 0x4800
	v_add_u32_e32 v200, s15, v66
	ds_read_b128 v[116:119], v248
	ds_read_b128 v[120:123], v248 offset:4608
	ds_read_b128 v[124:127], v249 offset:36864
	ds_read_b128 v[228:231], v249 offset:41472
	v_lshl_add_u64 v[164:165], v[114:115], 0, v[128:129]
	v_lshl_add_u64 v[168:169], v[74:75], 0, v[128:129]
	v_lshl_add_u64 v[172:173], v[112:113], 0, v[128:129]
	v_lshl_add_u64 v[180:181], v[72:73], 0, v[128:129]
	v_lshl_add_u64 v[184:185], v[76:77], 0, v[128:129]
	v_lshl_add_u64 v[188:189], v[68:69], 0, v[128:129]
	v_lshl_add_u64 v[192:193], v[78:79], 0, v[128:129]
	v_lshl_add_u64 v[196:197], v[70:71], 0, v[128:129]
	global_load_dwordx4 v[164:167], v[164:165], off offset:128
	global_load_dwordx4 v[168:171], v[168:169], off offset:128
	global_load_dwordx4 v[172:175], v[172:173], off offset:128
	global_load_dwordx4 v[180:183], v[180:181], off offset:128
	global_load_dwordx4 v[184:187], v[184:185], off offset:128
	global_load_dwordx4 v[188:191], v[188:189], off offset:128
	global_load_dwordx4 v[192:195], v[192:193], off offset:128
	global_load_dwordx4 v[196:199], v[196:197], off offset:128
	v_lshl_add_u64 v[114:115], v[114:115], 0, s[68:69]
	v_lshl_add_u64 v[74:75], v[74:75], 0, s[68:69]
	v_lshl_add_u64 v[112:113], v[112:113], 0, s[68:69]
	v_lshl_add_u64 v[72:73], v[72:73], 0, s[68:69]
	v_lshl_add_u64 v[76:77], v[76:77], 0, s[68:69]
	v_lshl_add_u64 v[68:69], v[68:69], 0, s[68:69]
	v_lshl_add_u64 v[78:79], v[78:79], 0, s[68:69]
	v_lshl_add_u64 v[70:71], v[70:71], 0, s[68:69]
	ds_read_b128 v[232:235], v248 offset:32
	ds_read_b128 v[236:239], v248 offset:4640
	ds_read_b128 v[240:243], v249 offset:36896
	ds_read_b128 v[244:247], v249 offset:41504
	s_waitcnt lgkmcnt(5)
	v_mfma_f32_32x32x16_bf16 v[48:63], v[116:119], v[124:127], v[48:63]
	s_waitcnt lgkmcnt(4)
	v_mfma_f32_32x32x16_bf16 v[16:31], v[116:119], v[228:231], v[16:31]
	s_waitcnt lgkmcnt(5)
	v_mfma_f32_32x32x16_bf16 v[32:47], v[120:123], v[124:127], v[32:47]
	s_waitcnt lgkmcnt(4)
	v_mfma_f32_32x32x16_bf16 v[0:15], v[120:123], v[228:231], v[0:15]
	ds_read_b128 v[116:119], v248 offset:64
	ds_read_b128 v[120:123], v248 offset:4672
	ds_read_b128 v[124:127], v249 offset:36928
	ds_read_b128 v[228:231], v249 offset:41536
	s_waitcnt lgkmcnt(5)
	v_mfma_f32_32x32x16_bf16 v[48:63], v[232:235], v[240:243], v[48:63]
	s_waitcnt lgkmcnt(4)
	v_mfma_f32_32x32x16_bf16 v[16:31], v[232:235], v[244:247], v[16:31]
	s_waitcnt lgkmcnt(5)
	v_mfma_f32_32x32x16_bf16 v[32:47], v[236:239], v[240:243], v[32:47]
	s_waitcnt lgkmcnt(4)
	v_mfma_f32_32x32x16_bf16 v[0:15], v[236:239], v[244:247], v[0:15]
	ds_read_b128 v[232:235], v248 offset:96
	ds_read_b128 v[236:239], v248 offset:4704
	ds_read_b128 v[240:243], v249 offset:36960
	ds_read_b128 v[244:247], v249 offset:41568
	s_waitcnt vmcnt(8) lgkmcnt(5)
	v_mfma_f32_32x32x16_bf16 v[48:63], v[116:119], v[124:127], v[48:63]
	ds_write_b128 v200, v[130:133]
	s_waitcnt lgkmcnt(5)
	v_mfma_f32_32x32x16_bf16 v[16:31], v[116:119], v[228:231], v[16:31]
	ds_write_b128 v200, v[134:137] offset:36864
	s_waitcnt lgkmcnt(7)
	v_mfma_f32_32x32x16_bf16 v[32:47], v[120:123], v[124:127], v[32:47]
	ds_write_b128 v200, v[138:141] offset:4608
	s_waitcnt lgkmcnt(7)
	v_mfma_f32_32x32x16_bf16 v[0:15], v[120:123], v[228:231], v[0:15]
	ds_write_b128 v200, v[142:145] offset:41472
	s_waitcnt lgkmcnt(5)
	v_mfma_f32_32x32x16_bf16 v[48:63], v[232:235], v[240:243], v[48:63]
	ds_write_b128 v200, v[146:149] offset:9216
	s_waitcnt lgkmcnt(5)
	v_mfma_f32_32x32x16_bf16 v[16:31], v[232:235], v[244:247], v[16:31]
	ds_write_b128 v200, v[150:153] offset:46080
	s_waitcnt lgkmcnt(7)
	v_mfma_f32_32x32x16_bf16 v[32:47], v[236:239], v[240:243], v[32:47]
	ds_write_b128 v200, v[154:157] offset:13824
	s_waitcnt lgkmcnt(7)
	v_mfma_f32_32x32x16_bf16 v[0:15], v[236:239], v[244:247], v[0:15]
	ds_write_b128 v200, v[158:161] offset:50688
	s_waitcnt lgkmcnt(0)
	s_barrier
	s_add_i32 s2, s2, 1
	s_cmp_lt_u32 s2, s14
	s_cbranch_scc1 .Lgt_top
	s_and_b32 s15, s2, 1
	s_mul_i32 s15, s15, 0x4800
	v_add_u32_e32 v248, s15, v64
	v_add_u32_e32 v249, s15, v65
	s_xor_b32 s15, s15, 0x4800
	v_add_u32_e32 v200, s15, v66
	ds_read_b128 v[116:119], v248
	ds_read_b128 v[120:123], v248 offset:4608
	ds_read_b128 v[124:127], v249 offset:36864
	ds_read_b128 v[228:231], v249 offset:41472
	ds_read_b128 v[232:235], v248 offset:32
	ds_read_b128 v[236:239], v248 offset:4640
	ds_read_b128 v[240:243], v249 offset:36896
	ds_read_b128 v[244:247], v249 offset:41504
	s_waitcnt lgkmcnt(5)
	v_mfma_f32_32x32x16_bf16 v[48:63], v[116:119], v[124:127], v[48:63]
	s_waitcnt lgkmcnt(4)
	v_mfma_f32_32x32x16_bf16 v[16:31], v[116:119], v[228:231], v[16:31]
	s_waitcnt lgkmcnt(5)
	v_mfma_f32_32x32x16_bf16 v[32:47], v[120:123], v[124:127], v[32:47]
	s_waitcnt lgkmcnt(4)
	v_mfma_f32_32x32x16_bf16 v[0:15], v[120:123], v[228:231], v[0:15]
	ds_read_b128 v[116:119], v248 offset:64
	ds_read_b128 v[120:123], v248 offset:4672
	ds_read_b128 v[124:127], v249 offset:36928
	ds_read_b128 v[228:231], v249 offset:41536
	s_waitcnt lgkmcnt(5)
	v_mfma_f32_32x32x16_bf16 v[48:63], v[232:235], v[240:243], v[48:63]
	s_waitcnt lgkmcnt(4)
	v_mfma_f32_32x32x16_bf16 v[16:31], v[232:235], v[244:247], v[16:31]
	s_waitcnt lgkmcnt(5)
	v_mfma_f32_32x32x16_bf16 v[32:47], v[236:239], v[240:243], v[32:47]
	s_waitcnt lgkmcnt(4)
	v_mfma_f32_32x32x16_bf16 v[0:15], v[236:239], v[244:247], v[0:15]
	ds_read_b128 v[232:235], v248 offset:96
	ds_read_b128 v[236:239], v248 offset:4704
	ds_read_b128 v[240:243], v249 offset:36960
	ds_read_b128 v[244:247], v249 offset:41568
	s_waitcnt vmcnt(0) lgkmcnt(5)
	v_mfma_f32_32x32x16_bf16 v[48:63], v[116:119], v[124:127], v[48:63]
	ds_write_b128 v200, v[164:167]
	s_waitcnt lgkmcnt(5)
	v_mfma_f32_32x32x16_bf16 v[16:31], v[116:119], v[228:231], v[16:31]
	ds_write_b128 v200, v[168:171] offset:36864
	s_waitcnt lgkmcnt(7)
	v_mfma_f32_32x32x16_bf16 v[32:47], v[120:123], v[124:127], v[32:47]
	ds_write_b128 v200, v[172:175] offset:4608
	s_waitcnt lgkmcnt(7)
	v_mfma_f32_32x32x16_bf16 v[0:15], v[120:123], v[228:231], v[0:15]
	ds_write_b128 v200, v[180:183] offset:41472
	s_waitcnt lgkmcnt(5)
	v_mfma_f32_32x32x16_bf16 v[48:63], v[232:235], v[240:243], v[48:63]
	ds_write_b128 v200, v[184:187] offset:9216
	s_waitcnt lgkmcnt(5)
	v_mfma_f32_32x32x16_bf16 v[16:31], v[232:235], v[244:247], v[16:31]
	ds_write_b128 v200, v[188:191] offset:46080
	s_waitcnt lgkmcnt(7)
	v_mfma_f32_32x32x16_bf16 v[32:47], v[236:239], v[240:243], v[32:47]
	ds_write_b128 v200, v[192:195] offset:13824
	s_waitcnt lgkmcnt(7)
	v_mfma_f32_32x32x16_bf16 v[0:15], v[236:239], v[244:247], v[0:15]
	ds_write_b128 v200, v[196:199] offset:50688
	s_waitcnt lgkmcnt(0)
	s_barrier
	s_add_i32 s2, s2, 1
	s_nop 7
	s_nop 7
	s_bitcmp1_b32 s24, 0
	s_cselect_b32 s2, 0x4800, 0
	v_add_u32_e32 v120, s2, v64
	v_add_u32_e32 v121, s2, v65
	ds_read_b128 v[64:67], v120 offset:4608
	ds_read_b128 v[68:71], v121 offset:41472
	ds_read_b128 v[72:75], v120
	ds_read_b128 v[76:79], v120 offset:32
	ds_read_b128 v[112:115], v121 offset:36864
	ds_read_b128 v[116:119], v121 offset:36896
	s_waitcnt lgkmcnt(3)
	v_mfma_f32_32x32x16_bf16 v[16:31], v[72:75], v[68:71], v[16:31]
	s_lshl_b32 s2, s29, 10
	s_add_i32 s2, s2, s4
	s_add_i32 s16, s2, 0x600
	s_cmpk_lt_i32 s2, 0x800
	s_cselect_b32 s16, s2, s16
	s_mov_b64 s[14:15], s[0:1]
	s_ashr_i32 s17, s16, 31
	s_waitcnt lgkmcnt(1)
	v_mfma_f32_32x32x16_bf16 v[48:63], v[72:75], v[112:115], v[48:63]
	s_lshl_b64 s[16:17], s[16:17], 1
	s_add_u32 s16, s30, s16
	s_addc_u32 s17, s31, s17
	v_mfma_f32_32x32x16_bf16 v[32:47], v[64:67], v[112:115], v[32:47]
	v_mov_b32_e32 v112, 1.0
	v_mov_b32_e32 v114, 1.0
	v_mfma_f32_32x32x16_bf16 v[0:15], v[64:67], v[68:71], v[0:15]
	ds_read_b128 v[64:67], v120 offset:4640
	ds_read_b128 v[68:71], v121 offset:41504
	s_waitcnt lgkmcnt(2)
	v_mfma_f32_32x32x16_bf16 v[48:63], v[76:79], v[116:119], v[48:63]
	s_waitcnt lgkmcnt(0)
	v_mfma_f32_32x32x16_bf16 v[16:31], v[76:79], v[68:71], v[16:31]
	v_mfma_f32_32x32x16_bf16 v[32:47], v[64:67], v[116:119], v[32:47]
	v_mfma_f32_32x32x16_bf16 v[0:15], v[64:67], v[68:71], v[0:15]
	ds_read_b128 v[64:67], v120 offset:64
	ds_read_b128 v[68:71], v120 offset:4672
	ds_read_b128 v[72:75], v121 offset:36928
	ds_read_b128 v[76:79], v121 offset:41536
	s_waitcnt lgkmcnt(1)
	v_mfma_f32_32x32x16_bf16 v[48:63], v[64:67], v[72:75], v[48:63]
	s_waitcnt lgkmcnt(0)
	v_mfma_f32_32x32x16_bf16 v[16:31], v[64:67], v[76:79], v[16:31]
	v_mfma_f32_32x32x16_bf16 v[32:47], v[68:71], v[72:75], v[32:47]
	v_mfma_f32_32x32x16_bf16 v[0:15], v[68:71], v[76:79], v[0:15]
	ds_read_b128 v[64:67], v120 offset:96
	ds_read_b128 v[68:71], v120 offset:4704
	ds_read_b128 v[72:75], v121 offset:36960
	ds_read_b128 v[76:79], v121 offset:41568
	s_waitcnt lgkmcnt(0)
	s_barrier
	s_load_dwordx2 s[14:15], s[14:15], 0x108
	s_waitcnt lgkmcnt(0)
	s_add_u32 s14, s14, 0x1d4d4000
	v_mfma_f32_32x32x16_bf16 v[48:63], v[64:67], v[72:75], v[48:63]
	s_addc_u32 s15, s15, 0
	s_cmp_eq_u32 s29, 1
	v_mfma_f32_32x32x16_bf16 v[16:31], v[64:67], v[76:79], v[16:31]
	v_mov_b32_e32 v64, v205
	s_nop 0
	v_lshlrev_b32_e32 v65, 4, v64
	v_and_b32_e32 v128, 0xf0, v65
	v_ashrrev_i32_e32 v65, 4, v64
	v_add_u32_e32 v66, s6, v65
	v_mfma_f32_32x32x16_bf16 v[32:47], v[68:71], v[72:75], v[32:47]
	v_and_b32_e32 v115, 0x5f, v64
	v_mfma_f32_32x32x16_bf16 v[0:15], v[68:71], v[76:79], v[0:15]
	v_lshl_add_u64 v[70:71], s[16:17], 0, v[128:129]
	v_mad_i64_i32 v[164:165], s[16:17], v66, s33, v[70:71]
	global_load_dwordx4 v[164:167], v[164:165], off
	v_mad_u64_u32 v[228:229], s[16:17], v65, s47, v[128:129]
	v_add_u32_e32 v65, 0x100, v64
	v_ashrrev_i32_e32 v65, 4, v65
	v_add_u32_e32 v168, s6, v65
	v_mad_i64_i32 v[168:169], s[16:17], v168, s33, v[70:71]
	global_load_dwordx4 v[168:171], v[168:169], off
	v_mad_u64_u32 v[230:231], s[16:17], v65, s47, v[128:129]
	v_add_u32_e32 v65, 0x200, v64
	v_ashrrev_i32_e32 v65, 4, v65
	v_add_u32_e32 v172, s6, v65
	v_mad_i64_i32 v[172:173], s[16:17], v172, s33, v[70:71]
	global_load_dwordx4 v[172:175], v[172:173], off
	v_mad_u64_u32 v[232:233], s[16:17], v65, s47, v[128:129]
	v_add_u32_e32 v65, 0x300, v64
	v_ashrrev_i32_e32 v65, 4, v65
	v_add_u32_e32 v180, s6, v65
	v_mad_i64_i32 v[180:181], s[16:17], v180, s33, v[70:71]
	global_load_dwordx4 v[180:183], v[180:181], off
	v_mad_u64_u32 v[234:235], s[16:17], v65, s47, v[128:129]
	v_add_u32_e32 v65, 0x400, v64
	v_ashrrev_i32_e32 v65, 4, v65
	v_add_u32_e32 v184, s6, v65
	v_mad_i64_i32 v[184:185], s[16:17], v184, s33, v[70:71]
	global_load_dwordx4 v[184:187], v[184:185], off
	v_mad_u64_u32 v[236:237], s[16:17], v65, s47, v[128:129]
	v_add_u32_e32 v65, 0x500, v64
	v_ashrrev_i32_e32 v65, 4, v65
	v_add_u32_e32 v188, s6, v65
	v_mad_i64_i32 v[188:189], s[16:17], v188, s33, v[70:71]
	global_load_dwordx4 v[188:191], v[188:189], off
	v_mad_u64_u32 v[238:239], s[16:17], v65, s47, v[128:129]
	v_add_u32_e32 v65, 0x600, v64
	v_ashrrev_i32_e32 v65, 4, v65
	v_add_u32_e32 v192, s6, v65
	v_mad_i64_i32 v[192:193], s[16:17], v192, s33, v[70:71]
	global_load_dwordx4 v[192:195], v[192:193], off
	v_mad_u64_u32 v[72:73], s[16:17], v65, s47, v[128:129]
	v_add_u32_e32 v65, 0x700, v64
	v_ashrrev_i32_e32 v65, 4, v65
	v_add_u32_e32 v66, s6, v65
	v_mad_i64_i32 v[66:67], s[16:17], v66, s33, v[70:71]
	global_load_dwordx4 v[66:69], v[66:67], off
	v_mad_u64_u32 v[70:71], s[16:17], v65, s47, v[128:129]
	s_cselect_b64 s[16:17], -1, 0
	s_and_b64 vcc, exec, s[16:17]
	s_waitcnt vmcnt(7)
	ds_write_b128 v228, v[164:167]
	s_waitcnt vmcnt(6)
	ds_write_b128 v230, v[168:171]
	s_waitcnt vmcnt(5)
	ds_write_b128 v232, v[172:175]
	s_waitcnt vmcnt(4)
	ds_write_b128 v234, v[180:183]
	s_waitcnt vmcnt(3)
	ds_write_b128 v236, v[184:187]
	s_waitcnt vmcnt(2)
	ds_write_b128 v238, v[188:191]
	s_waitcnt vmcnt(1)
	ds_write_b128 v72, v[192:195]
	s_waitcnt vmcnt(0)
	ds_write_b128 v70, v[66:69]
	s_waitcnt lgkmcnt(0)
	s_barrier
	s_cbranch_vccz .LBB0_1868
	v_or_b32_e32 v66, s6, v115
	v_ashrrev_i32_e32 v67, 31, v66
	v_lshl_add_u64 v[66:67], v[66:67], 2, s[14:15]
	global_load_dword v114, v[66:67], off
